# previous + MoE gate/up phase: weight-conversion share taken by all blocks when fewer than 128 blocks are idle in the last GEMM round
# speedup vs baseline: 1.0020x; 1.0002x over previous
;     ...
;   if (cvp && cv0 < cv1) {
;     int n_idle = 0, my_idx = -1;
; #pragma unroll
;     for (int x = 0; x < 8; ++x) {
;       const int sx = (int)(((long long)T * x) >> 3), ex = (int)(((long long)T * (x + 1)) >> 3), rem = (ex - sx) % nbx;
;       if (rem) { if (x == xcd && li >= rem) my_idx = n_idle + (li - rem); n_idle += nbx - rem; }
;     }
;     if (n_idle == 0) conv_range(*cvp, cv0, cv1, sm);
;     else if (my_idx >= 0) conv_range(*cvp, cv0, cv1, sm, my_idx, n_idle);
.LBB0_2144:
	s_cmp_ge_u32 s18, 0x80
	s_cbranch_scc0 .LBB0_2163
	s_mov_b64 s[0:1], 0
	s_cmp_gt_i32 s3, -1
	s_mov_b64 s[14:15], 0
	s_cbranch_scc0 .LBB0_2164
	v_mov_b32_e32 v16, v203
	s_cmpk_lt_u32 s3, 0xa30
	s_mov_b64 s[14:15], -1
	s_cbranch_scc1 .LBB0_2148
	s_mov_b64 s[14:15], 0
	s_barrier
